# P0 W_in items: gain applied after the LDS transpose (2 gain loads per item), all 32 weight loads in flight
# speedup vs baseline: 1.0112x; 1.0031x over previous
; #define LAS __attribute__((address_space(3)))
; #define LDS_WAIT() asm volatile("s_waitcnt lgkmcnt(0)" ::: "memory")
; __device__ __forceinline__ unsigned pk2(float lo, float hi) { unsigned r; asm("v_cvt_pk_bf16_f32 %0, %1, %2" : "=v"(r) : "v"(lo), "v"(hi)); return r; }
; __device__ __forceinline__ void p0_transpose_item(const float* W, int K, int N, bf16_t* WT, LAS float* scr, int item, int lane, const float* kscale) {
;     ...
;     const int c = lane & 7;
; #pragma unroll
;     for (int j = 0; j < 4; ++j) { const int n = (lane >> 3) + 8 * j; const LAS float* s = scr + (8 * c) * 33 + n;
;         v4u o; o.x = pk2(s[0 * 33], s[1 * 33]); o.y = pk2(s[2 * 33], s[3 * 33]); o.z = pk2(s[4 * 33], s[5 * 33]); o.w = pk2(s[6 * 33], s[7 * 33]);
;         *(v4u*)(WT + (size_t)(n0 + n) * K + k0 + 8 * c) = o; }
;     LDS_WAIT(); asm volatile("" ::: "memory");
.LBB0_224:
	s_mul_i32 s1, s2, 0x1a00000
	s_waitcnt lgkmcnt(0)
	s_mul_hi_i32 s0, s2, 0x1a00000
	s_add_u32 s2, s94, s1
	s_addc_u32 s3, s95, s0
	s_lshl_b64 s[0:1], s[20:21], 1
	ds_read2_b32 v[18:19], v9 offset0:33 offset1:41
	ds_read2_b32 v[20:21], v9 offset1:8
	ds_read2_b32 v[22:23], v9 offset0:66 offset1:74
	ds_read2_b32 v[24:25], v9 offset0:99 offset1:107
	ds_read2_b32 v[26:27], v9 offset0:132 offset1:140
	ds_read2_b32 v[28:29], v9 offset0:165 offset1:173
	ds_read2_b32 v[30:31], v9 offset0:198 offset1:206
	ds_read2_b32 v[32:33], v9 offset0:231 offset1:239
	ds_read2_b32 v[152:153], v9 offset0:16 offset1:24
	ds_read2_b32 v[154:155], v9 offset0:49 offset1:57
	ds_read2_b32 v[156:157], v9 offset0:82 offset1:90
	ds_read2_b32 v[158:159], v9 offset0:115 offset1:123
	ds_read2_b32 v[160:161], v9 offset0:148 offset1:156
	ds_read2_b32 v[162:163], v9 offset0:181 offset1:189
	ds_read2_b32 v[164:165], v9 offset0:214 offset1:222
	ds_read2_b32 v[166:167], v9 offset0:247 offset1:255
	s_add_u32 s0, s2, s0
	s_addc_u32 s1, s3, s1
	v_lshlrev_b32_e32 v0, 1, v8
	v_lshl_add_u64 v[34:35], s[0:1], 0, v[0:1]
	v_or_b32_e32 v48, s16, v7
	v_ashrrev_i32_e32 v49, 31, v48
	v_lshlrev_b64 v[48:49], 12, v[48:49]
	v_lshl_add_u64 v[48:49], v[34:35], 0, v[48:49]
	v_or_b32_e32 v168, s16, v36
	v_ashrrev_i32_e32 v169, 31, v168
	v_lshlrev_b64 v[168:169], 12, v[168:169]
	v_lshl_add_u64 v[168:169], v[34:35], 0, v[168:169]
	v_or_b32_e32 v170, s16, v37
	v_ashrrev_i32_e32 v171, 31, v170
	v_lshlrev_b64 v[170:171], 12, v[170:171]
	v_lshl_add_u64 v[170:171], v[34:35], 0, v[170:171]
	v_or_b32_e32 v172, s16, v38
	v_ashrrev_i32_e32 v173, 31, v172
	v_lshlrev_b64 v[172:173], 12, v[172:173]
	v_lshl_add_u64 v[172:173], v[34:35], 0, v[172:173]
	s_waitcnt lgkmcnt(0)
	v_mul_f32_e32 v20, v20, v132
	v_mul_f32_e32 v21, v21, v132
	v_mul_f32_e32 v152, v152, v132
	v_mul_f32_e32 v153, v153, v132
	v_mul_f32_e32 v18, v18, v133
	v_mul_f32_e32 v19, v19, v133
	v_mul_f32_e32 v154, v154, v133
	v_mul_f32_e32 v155, v155, v133
	v_mul_f32_e32 v22, v22, v134
	v_mul_f32_e32 v23, v23, v134
	v_mul_f32_e32 v156, v156, v134
	v_mul_f32_e32 v157, v157, v134
	v_mul_f32_e32 v24, v24, v135
	v_mul_f32_e32 v25, v25, v135
	v_mul_f32_e32 v158, v158, v135
	v_mul_f32_e32 v159, v159, v135
	v_mul_f32_e32 v26, v26, v136
	v_mul_f32_e32 v27, v27, v136
	v_mul_f32_e32 v160, v160, v136
	v_mul_f32_e32 v161, v161, v136
	v_mul_f32_e32 v28, v28, v137
	v_mul_f32_e32 v29, v29, v137
	v_mul_f32_e32 v162, v162, v137
	v_mul_f32_e32 v163, v163, v137
	v_mul_f32_e32 v30, v30, v138
	v_mul_f32_e32 v31, v31, v138
	v_mul_f32_e32 v164, v164, v138
	v_mul_f32_e32 v165, v165, v138
	v_mul_f32_e32 v32, v32, v139
	v_mul_f32_e32 v33, v33, v139
	v_mul_f32_e32 v166, v166, v139
	v_mul_f32_e32 v167, v167, v139
	v_cvt_pk_bf16_f32 v14, v20, v18
	v_cvt_pk_bf16_f32 v15, v22, v24
	v_cvt_pk_bf16_f32 v16, v26, v28
	v_cvt_pk_bf16_f32 v17, v30, v32
	v_cvt_pk_bf16_f32 v140, v21, v19
	v_cvt_pk_bf16_f32 v141, v23, v25
	v_cvt_pk_bf16_f32 v142, v27, v29
	v_cvt_pk_bf16_f32 v143, v31, v33
	v_cvt_pk_bf16_f32 v144, v152, v154
	v_cvt_pk_bf16_f32 v145, v156, v158
	v_cvt_pk_bf16_f32 v146, v160, v162
	v_cvt_pk_bf16_f32 v147, v164, v166
	v_cvt_pk_bf16_f32 v148, v153, v155
	v_cvt_pk_bf16_f32 v149, v157, v159
	v_cvt_pk_bf16_f32 v150, v161, v163
	v_cvt_pk_bf16_f32 v151, v165, v167
	global_store_dwordx4 v[48:49], v[14:17], off
	global_store_dwordx4 v[168:169], v[140:143], off
	global_store_dwordx4 v[170:171], v[144:147], off
	global_store_dwordx4 v[172:173], v[148:151], off

; #define LAS __attribute__((address_space(3)))
; #define LDS_WAIT() asm volatile("s_waitcnt lgkmcnt(0)" ::: "memory")
; __device__ __forceinline__ void p0_transpose_item(const float* W, int K, int N, bf16_t* WT, LAS float* scr, int item, int lane, const float* kscale) {
;     const int nblk = N / 32, kb = item / nblk, nb = item % nblk, k0 = 64 * kb, n0 = 32 * nb;
; #pragma unroll 8
;     for (int i = 0; i < 32; ++i) { const int kk = 2 * i + (lane >> 5); scr[kk * 33 + (lane & 31)] = W[(size_t)(k0 + kk) * N + n0 + (lane & 31)] * (kscale ? kscale[k0 + kk] : 1.0f); }
;     LDS_WAIT(); asm volatile("" ::: "memory");
.LBB0_230:
	s_and_b64 vcc, exec, s[0:1]
	s_cbranch_vccz .LBB0_225
	s_lshl_b64 s[0:1], s[2:3], 13
	s_add_u32 s18, s54, s0
	s_mul_i32 s0, s5, 0x4ec5
	s_addc_u32 s19, s55, s1
	s_lshr_b32 s1, s0, 31
	s_ashr_i32 s0, s0, 22
	s_add_i32 s0, s0, s1
	s_mul_i32 s1, s0, 0xd0
	s_sub_i32 s1, s5, s1
	s_sext_i32_i16 s1, s1
	s_lshl_b32 s16, s1, 5
	s_lshl_b32 s20, s0, 6
	s_ashr_i32 s17, s16, 31
	s_mul_i32 s7, s2, 0x3400000
	s_ashr_i32 s21, s20, 31
	s_lshl_b64 s[0:1], s[16:17], 2
	s_mul_hi_i32 s6, s2, 0x3400000
	s_add_u32 s0, s0, s7
	s_addc_u32 s1, s1, s6
	s_mul_i32 s8, s20, 0x6800
	s_add_u32 s6, s56, s0
	s_addc_u32 s7, s57, s1
	s_add_u32 s6, s6, s8
	s_addc_u32 s7, s7, 0
	v_mov_b32_e32 v47, 0x6800
	v_mad_u32_u24 v47, v4, v47, v12
	v_add_u32_e32 v32, s20, v8
	v_lshlrev_b32_e32 v32, 2, v32
	global_load_dwordx4 v[132:135], v32, s[18:19]
	global_load_dwordx4 v[136:139], v32, s[18:19] offset:16
	global_load_dword v100, v47, s[6:7]
	s_add_u32 s6, s6, 0xd000
	s_addc_u32 s7, s7, 0
	global_load_dword v101, v47, s[6:7]
	s_add_u32 s6, s6, 0xd000
	s_addc_u32 s7, s7, 0
	global_load_dword v102, v47, s[6:7]
	s_add_u32 s6, s6, 0xd000
	s_addc_u32 s7, s7, 0
	global_load_dword v103, v47, s[6:7]
	s_add_u32 s6, s6, 0xd000
	s_addc_u32 s7, s7, 0
	global_load_dword v104, v47, s[6:7]
	s_add_u32 s6, s6, 0xd000
	s_addc_u32 s7, s7, 0
	global_load_dword v105, v47, s[6:7]
	s_add_u32 s6, s6, 0xd000
	s_addc_u32 s7, s7, 0
	global_load_dword v106, v47, s[6:7]
	s_add_u32 s6, s6, 0xd000
	s_addc_u32 s7, s7, 0
	global_load_dword v107, v47, s[6:7]
	s_add_u32 s6, s6, 0xd000
	s_addc_u32 s7, s7, 0
	global_load_dword v108, v47, s[6:7]
	s_add_u32 s6, s6, 0xd000
	s_addc_u32 s7, s7, 0
	global_load_dword v109, v47, s[6:7]
	s_add_u32 s6, s6, 0xd000
	s_addc_u32 s7, s7, 0
	global_load_dword v110, v47, s[6:7]
	s_add_u32 s6, s6, 0xd000
	s_addc_u32 s7, s7, 0
	global_load_dword v111, v47, s[6:7]
	s_add_u32 s6, s6, 0xd000
	s_addc_u32 s7, s7, 0
	global_load_dword v112, v47, s[6:7]
	s_add_u32 s6, s6, 0xd000
	s_addc_u32 s7, s7, 0
	global_load_dword v113, v47, s[6:7]
	s_add_u32 s6, s6, 0xd000
	s_addc_u32 s7, s7, 0
	global_load_dword v114, v47, s[6:7]
	s_add_u32 s6, s6, 0xd000
	s_addc_u32 s7, s7, 0
	global_load_dword v115, v47, s[6:7]
	s_add_u32 s6, s6, 0xd000
	s_addc_u32 s7, s7, 0
	global_load_dword v116, v47, s[6:7]
	s_add_u32 s6, s6, 0xd000
	s_addc_u32 s7, s7, 0
	global_load_dword v117, v47, s[6:7]
	s_add_u32 s6, s6, 0xd000
	s_addc_u32 s7, s7, 0
	global_load_dword v118, v47, s[6:7]
	s_add_u32 s6, s6, 0xd000
	s_addc_u32 s7, s7, 0
	global_load_dword v119, v47, s[6:7]
	s_add_u32 s6, s6, 0xd000
	s_addc_u32 s7, s7, 0
	global_load_dword v120, v47, s[6:7]
	s_add_u32 s6, s6, 0xd000
	s_addc_u32 s7, s7, 0
	global_load_dword v121, v47, s[6:7]
	s_add_u32 s6, s6, 0xd000
	s_addc_u32 s7, s7, 0
	global_load_dword v122, v47, s[6:7]
	s_add_u32 s6, s6, 0xd000
	s_addc_u32 s7, s7, 0
	global_load_dword v123, v47, s[6:7]
	s_add_u32 s6, s6, 0xd000
	s_addc_u32 s7, s7, 0
	global_load_dword v124, v47, s[6:7]
	s_add_u32 s6, s6, 0xd000
	s_addc_u32 s7, s7, 0
	global_load_dword v125, v47, s[6:7]
	s_add_u32 s6, s6, 0xd000
	s_addc_u32 s7, s7, 0
	global_load_dword v126, v47, s[6:7]
	s_add_u32 s6, s6, 0xd000
	s_addc_u32 s7, s7, 0
	global_load_dword v127, v47, s[6:7]
	s_add_u32 s6, s6, 0xd000
	s_addc_u32 s7, s7, 0
	global_load_dword v128, v47, s[6:7]
	s_add_u32 s6, s6, 0xd000
	s_addc_u32 s7, s7, 0
	global_load_dword v129, v47, s[6:7]
	s_add_u32 s6, s6, 0xd000
	s_addc_u32 s7, s7, 0
	global_load_dword v130, v47, s[6:7]
	s_add_u32 s6, s6, 0xd000
	s_addc_u32 s7, s7, 0
	global_load_dword v131, v47, s[6:7]
	s_waitcnt vmcnt(31)
	ds_write_b32 v39, v100 offset:0
	s_waitcnt vmcnt(30)
	ds_write_b32 v39, v101 offset:264
	s_waitcnt vmcnt(29)
	ds_write_b32 v39, v102 offset:528
	s_waitcnt vmcnt(28)
	ds_write_b32 v39, v103 offset:792
	s_waitcnt vmcnt(27)
	ds_write_b32 v39, v104 offset:1056
	s_waitcnt vmcnt(26)
	ds_write_b32 v39, v105 offset:1320
	s_waitcnt vmcnt(25)
	ds_write_b32 v39, v106 offset:1584
	s_waitcnt vmcnt(24)
	ds_write_b32 v39, v107 offset:1848
	s_waitcnt vmcnt(23)
	ds_write_b32 v39, v108 offset:2112
	s_waitcnt vmcnt(22)
	ds_write_b32 v39, v109 offset:2376
	s_waitcnt vmcnt(21)
	ds_write_b32 v39, v110 offset:2640
	s_waitcnt vmcnt(20)
	ds_write_b32 v39, v111 offset:2904
	s_waitcnt vmcnt(19)
	ds_write_b32 v39, v112 offset:3168
	s_waitcnt vmcnt(18)
	ds_write_b32 v39, v113 offset:3432
	s_waitcnt vmcnt(17)
	ds_write_b32 v39, v114 offset:3696
	s_waitcnt vmcnt(16)
	ds_write_b32 v39, v115 offset:3960
	s_waitcnt vmcnt(15)
	ds_write_b32 v39, v116 offset:4224
	s_waitcnt vmcnt(14)
	ds_write_b32 v39, v117 offset:4488
	s_waitcnt vmcnt(13)
	ds_write_b32 v39, v118 offset:4752
	s_waitcnt vmcnt(12)
	ds_write_b32 v39, v119 offset:5016
	s_waitcnt vmcnt(11)
	ds_write_b32 v39, v120 offset:5280
	s_waitcnt vmcnt(10)
	ds_write_b32 v39, v121 offset:5544
	s_waitcnt vmcnt(9)
	ds_write_b32 v39, v122 offset:5808
	s_waitcnt vmcnt(8)
	ds_write_b32 v39, v123 offset:6072
	s_waitcnt vmcnt(7)
	ds_write_b32 v39, v124 offset:6336
	s_waitcnt vmcnt(6)
	ds_write_b32 v39, v125 offset:6600
	s_waitcnt vmcnt(5)
	ds_write_b32 v39, v126 offset:6864
	s_waitcnt vmcnt(4)
	ds_write_b32 v39, v127 offset:7128
	s_waitcnt vmcnt(3)
	ds_write_b32 v39, v128 offset:7392
	s_waitcnt vmcnt(2)
	ds_write_b32 v39, v129 offset:7656
	s_waitcnt vmcnt(1)
	ds_write_b32 v39, v130 offset:7920
	s_waitcnt vmcnt(0)
	ds_write_b32 v39, v131 offset:8184
	s_branch .LBB0_224
